# GEMM K loops: dropped the hand loop's first s_barrier (the compiler's prologue already ends with its own wait + barrier)
# speedup vs baseline: 1.0002x; 1.0002x over previous
; #define LGKM0_BAR asm volatile("s_waitcnt lgkmcnt(0)\n\ts_barrier" ::: "memory");
; __device__ __forceinline__ void gemm256_tile(const u16* Ab, int lda, const u16* Bb, int ldb, int K, char* smem,
;                                              f32x16 (&acc)[2][4]) {
;     ...
;   const int xsw = (lane >> 2) & 3, hh = lane >> 5;
;   const unsigned fo0 = (unsigned)((hh ^ xsw) * 16), fo1 = (unsigned)(((2 + hh) ^ xsw) * 16);
;   const unsigned fa = (unsigned)((wm * 64 + (lane & 31)) * 64);
;   const unsigned fb = (unsigned)(16384 + (wn * 128 + (lane & 31)) * 64);
;     ...
;   asm volatile("s_waitcnt vmcnt(0)" ::: "memory");
;   const bool h1 = __builtin_amdgcn_readfirstlane(wid) >= 4;
;     ...
;   DMA_STAGE(0)
;   if (nks > 1) DMA_STAGE(1)
;   if (nks > 2) DMA_STAGE(2)
;   if (nks > 3) DMA_STAGE(3)
;   if (nks > 3)      asm volatile("s_waitcnt vmcnt(12)\n\ts_barrier" ::: "memory");
;   else if (nks > 2) asm volatile("s_waitcnt vmcnt(8)\n\ts_barrier" ::: "memory");
;   else if (nks > 1) asm volatile("s_waitcnt vmcnt(4)\n\ts_barrier" ::: "memory");
;   else              asm volatile("s_waitcnt vmcnt(0)\n\ts_barrier" ::: "memory");
;   bf16x8 afA[2], bfA[4], afB[2], bfB[4];
;   if (!h1) {
;     G_FRAGS(afA, bfA, 0, fo0)
;     LGKM0_BAR
;     for (int s = 0; s < nks; ++s) {
;       const int q = s & 3;
;       G_MMA(afA, bfA)
;       __builtin_amdgcn_sched_barrier(0);
;       LGKM0_BAR
;       G_FRAGS(afB, bfB, q, fo1)
;       __builtin_amdgcn_sched_barrier(0);
;       LGKM0_BAR
;       G_MMA(afB, bfB)
;       __builtin_amdgcn_sched_barrier(0);
;       G_WAIT_BAR(s)
;       if (s + 4 < nks) DMA_STAGE(s + 4)
;       if (s + 1 < nks) G_FRAGS(afA, bfA, (s + 1) & 3, fo0)
;       __builtin_amdgcn_sched_barrier(0);
;       LGKM0_BAR
;     }
.LBB0_197:
	v_lshrrev_b32_e32 v192, 6, v152
	v_bfe_u32 v193, v152, 2, 2
	v_readfirstlane_b32 s98, v192
	v_bfe_u32 v194, v152, 5, 1
	v_xor_b32_e32 v193, v194, v193
	v_lshlrev_b32_e32 v193, 4, v193
	v_xor_b32_e32 v194, 32, v193
	v_and_b32_e32 v195, 31, v152
	v_lshrrev_b32_e32 v196, 7, v152
	v_lshl_add_u32 v196, v196, 6, v195
	v_lshlrev_b32_e32 v196, 6, v196
	v_bfe_u32 v197, v152, 6, 1
	v_lshl_add_u32 v197, v197, 7, v195
	v_lshlrev_b32_e32 v197, 6, v197
	v_add3_u32 v154, v196, v193, 16
	v_add3_u32 v253, v196, v194, 16
	v_add3_u32 v254, v197, v193, 16
	v_add3_u32 v255, v197, v194, 16
	s_lshl_b32 s98, s98, 10
	s_add_u32 s98, s98, 16
	v_lshl_add_u64 v[164:165], 64, 2, v[164:165]
	v_lshl_add_u64 v[160:161], 64, 2, v[160:161]
	v_lshl_add_u64 v[166:167], 64, 2, v[166:167]
	v_lshl_add_u64 v[162:163], 64, 2, v[162:163]
	ds_read_b128 v[128:131], v154
	ds_read_b128 v[132:135], v154 offset:2048
	ds_read_b128 v[136:139], v254 offset:16384
	ds_read_b128 v[140:143], v254 offset:18432
	ds_read_b128 v[144:147], v254 offset:20480
	ds_read_b128 v[148:151], v254 offset:22528
	s_waitcnt lgkmcnt(0)
	v_mfma_f32_32x32x16_bf16 v[112:127], v[128:131], v[136:139], 0
	v_mfma_f32_32x32x16_bf16 v[96:111], v[128:131], v[140:143], 0
	ds_read_b128 v[192:195], v253
	ds_read_b128 v[196:199], v253 offset:2048
	v_mfma_f32_32x32x16_bf16 v[80:95], v[128:131], v[144:147], 0
	ds_read_b128 v[200:203], v255 offset:16384
	ds_read_b128 v[206:209], v255 offset:18432
	v_mfma_f32_32x32x16_bf16 v[64:79], v[128:131], v[148:151], 0
	ds_read_b128 v[210:213], v255 offset:20480
	ds_read_b128 v[214:217], v255 offset:22528
	v_mfma_f32_32x32x16_bf16 v[48:63], v[132:135], v[136:139], 0
	v_mfma_f32_32x32x16_bf16 v[32:47], v[132:135], v[140:143], 0
	v_mfma_f32_32x32x16_bf16 v[16:31], v[132:135], v[144:147], 0
	v_mfma_f32_32x32x16_bf16 v[0:15], v[132:135], v[148:151], 0
	s_waitcnt vmcnt(8)
	s_waitcnt lgkmcnt(0)
	s_barrier
	ds_read_b128 v[128:131], v154 offset:32768
	ds_read_b128 v[132:135], v154 offset:34816
	ds_read_b128 v[136:139], v254 offset:49152
	ds_read_b128 v[140:143], v254 offset:51200
	ds_read_b128 v[144:147], v254 offset:53248
	ds_read_b128 v[148:151], v254 offset:55296
	v_xor_b32_e32 v154, 0x10000, v154
	v_xor_b32_e32 v254, 0x10000, v254
	s_add_u32 m0, s98, 0x0
	v_mfma_f32_32x32x16_bf16 v[112:127], v[192:195], v[200:203], v[112:127]
	global_load_lds_dwordx4 v[164:165], off
	v_mfma_f32_32x32x16_bf16 v[96:111], v[192:195], v[206:209], v[96:111]
	s_add_u32 m0, s98, 0x2000
	v_mfma_f32_32x32x16_bf16 v[80:95], v[192:195], v[210:213], v[80:95]
	global_load_lds_dwordx4 v[160:161], off
	v_mfma_f32_32x32x16_bf16 v[64:79], v[192:195], v[214:217], v[64:79]
	s_add_u32 m0, s98, 0x4000
	v_mfma_f32_32x32x16_bf16 v[48:63], v[196:199], v[200:203], v[48:63]
	global_load_lds_dwordx4 v[166:167], off
	v_mfma_f32_32x32x16_bf16 v[32:47], v[196:199], v[206:209], v[32:47]
	s_add_u32 m0, s98, 0x6000
	v_mfma_f32_32x32x16_bf16 v[16:31], v[196:199], v[210:213], v[16:31]
	global_load_lds_dwordx4 v[162:163], off
	v_mfma_f32_32x32x16_bf16 v[0:15], v[196:199], v[214:217], v[0:15]
	v_lshl_add_u64 v[164:165], v[164:165], 0, 64
	v_lshl_add_u64 v[160:161], v[160:161], 0, 64
	v_lshl_add_u64 v[166:167], v[166:167], 0, 64
	v_lshl_add_u64 v[162:163], v[162:163], 0, 64
	s_waitcnt lgkmcnt(0)
	v_mfma_f32_32x32x16_bf16 v[112:127], v[128:131], v[136:139], v[112:127]
	v_mfma_f32_32x32x16_bf16 v[96:111], v[128:131], v[140:143], v[96:111]
	ds_read_b128 v[192:195], v253 offset:32768
	ds_read_b128 v[196:199], v253 offset:34816
	v_mfma_f32_32x32x16_bf16 v[80:95], v[128:131], v[144:147], v[80:95]
	ds_read_b128 v[200:203], v255 offset:49152
	ds_read_b128 v[206:209], v255 offset:51200
	v_mfma_f32_32x32x16_bf16 v[64:79], v[128:131], v[148:151], v[64:79]
	ds_read_b128 v[210:213], v255 offset:53248
	ds_read_b128 v[214:217], v255 offset:55296
	v_mfma_f32_32x32x16_bf16 v[48:63], v[132:135], v[136:139], v[48:63]
	v_mfma_f32_32x32x16_bf16 v[32:47], v[132:135], v[140:143], v[32:47]
	v_mfma_f32_32x32x16_bf16 v[16:31], v[132:135], v[144:147], v[16:31]
	v_mfma_f32_32x32x16_bf16 v[0:15], v[132:135], v[148:151], v[0:15]
	v_xor_b32_e32 v253, 0x10000, v253
	v_xor_b32_e32 v255, 0x10000, v255
	s_waitcnt vmcnt(8)
	s_waitcnt lgkmcnt(0)
	s_barrier
; #define LGKM0_BAR asm volatile("s_waitcnt lgkmcnt(0)\n\ts_barrier" ::: "memory");
; __device__ __forceinline__ void gemm256_tile(const u16* Ab, int lda, const u16* Bb, int ldb, int K, char* smem,
;                                              f32x16 (&acc)[2][4]) {
;     ...
;     for (int s = 0; s < nks; ++s) {
;       const int q = s & 3;
;       G_MMA(afA, bfA)
;       __builtin_amdgcn_sched_barrier(0);
;       LGKM0_BAR
;       G_FRAGS(afB, bfB, q, fo1)
;       __builtin_amdgcn_sched_barrier(0);
;       LGKM0_BAR
;       G_MMA(afB, bfB)
;       __builtin_amdgcn_sched_barrier(0);
;       G_WAIT_BAR(s)
;       if (s + 4 < nks) DMA_STAGE(s + 4)
;       if (s + 1 < nks) G_FRAGS(afA, bfA, (s + 1) & 3, fo0)
;       __builtin_amdgcn_sched_barrier(0);
;       LGKM0_BAR
;     }
	ds_read_b128 v[128:131], v154
	ds_read_b128 v[132:135], v154 offset:2048
	ds_read_b128 v[136:139], v254 offset:16384
	ds_read_b128 v[140:143], v254 offset:18432
	ds_read_b128 v[144:147], v254 offset:20480
	ds_read_b128 v[148:151], v254 offset:22528
	s_add_u32 m0, s98, 0x8000
	v_mfma_f32_32x32x16_bf16 v[112:127], v[192:195], v[200:203], v[112:127]
	global_load_lds_dwordx4 v[164:165], off
	v_mfma_f32_32x32x16_bf16 v[96:111], v[192:195], v[206:209], v[96:111]
	s_add_u32 m0, s98, 0xa000
	v_mfma_f32_32x32x16_bf16 v[80:95], v[192:195], v[210:213], v[80:95]
	global_load_lds_dwordx4 v[160:161], off
	v_mfma_f32_32x32x16_bf16 v[64:79], v[192:195], v[214:217], v[64:79]
	s_add_u32 m0, s98, 0xc000
	v_mfma_f32_32x32x16_bf16 v[48:63], v[196:199], v[200:203], v[48:63]
	global_load_lds_dwordx4 v[166:167], off
	v_mfma_f32_32x32x16_bf16 v[32:47], v[196:199], v[206:209], v[32:47]
	s_add_u32 m0, s98, 0xe000
	v_mfma_f32_32x32x16_bf16 v[16:31], v[196:199], v[210:213], v[16:31]
	global_load_lds_dwordx4 v[162:163], off
	v_mfma_f32_32x32x16_bf16 v[0:15], v[196:199], v[214:217], v[0:15]
	v_lshl_add_u64 v[164:165], v[164:165], 0, 64
	v_lshl_add_u64 v[160:161], v[160:161], 0, 64
	v_lshl_add_u64 v[166:167], v[166:167], 0, 64
	v_lshl_add_u64 v[162:163], v[162:163], 0, 64
	s_waitcnt lgkmcnt(0)
	v_mfma_f32_32x32x16_bf16 v[112:127], v[128:131], v[136:139], v[112:127]
	v_mfma_f32_32x32x16_bf16 v[96:111], v[128:131], v[140:143], v[96:111]
	ds_read_b128 v[192:195], v253
	ds_read_b128 v[196:199], v253 offset:2048
	v_mfma_f32_32x32x16_bf16 v[80:95], v[128:131], v[144:147], v[80:95]
	ds_read_b128 v[200:203], v255 offset:16384
	ds_read_b128 v[206:209], v255 offset:18432
	v_mfma_f32_32x32x16_bf16 v[64:79], v[128:131], v[148:151], v[64:79]
	ds_read_b128 v[210:213], v255 offset:20480
	ds_read_b128 v[214:217], v255 offset:22528
	v_mfma_f32_32x32x16_bf16 v[48:63], v[132:135], v[136:139], v[48:63]
	v_mfma_f32_32x32x16_bf16 v[32:47], v[132:135], v[140:143], v[32:47]
	v_mfma_f32_32x32x16_bf16 v[16:31], v[132:135], v[144:147], v[16:31]
	v_mfma_f32_32x32x16_bf16 v[0:15], v[132:135], v[148:151], v[0:15]
	s_waitcnt vmcnt(8)
	s_waitcnt lgkmcnt(0)
	s_barrier
	ds_read_b128 v[128:131], v154 offset:32768
	ds_read_b128 v[132:135], v154 offset:34816
	ds_read_b128 v[136:139], v254 offset:49152
	ds_read_b128 v[140:143], v254 offset:51200
	ds_read_b128 v[144:147], v254 offset:53248
	ds_read_b128 v[148:151], v254 offset:55296
	v_xor_b32_e32 v154, 0x10000, v154
	v_xor_b32_e32 v254, 0x10000, v254
	s_add_u32 m0, s98, 0x10000
	v_mfma_f32_32x32x16_bf16 v[112:127], v[192:195], v[200:203], v[112:127]
	global_load_lds_dwordx4 v[164:165], off
	v_mfma_f32_32x32x16_bf16 v[96:111], v[192:195], v[206:209], v[96:111]
	s_add_u32 m0, s98, 0x12000
	v_mfma_f32_32x32x16_bf16 v[80:95], v[192:195], v[210:213], v[80:95]
	global_load_lds_dwordx4 v[160:161], off
	v_mfma_f32_32x32x16_bf16 v[64:79], v[192:195], v[214:217], v[64:79]
	s_add_u32 m0, s98, 0x14000
	v_mfma_f32_32x32x16_bf16 v[48:63], v[196:199], v[200:203], v[48:63]
	global_load_lds_dwordx4 v[166:167], off
	v_mfma_f32_32x32x16_bf16 v[32:47], v[196:199], v[206:209], v[32:47]
	s_add_u32 m0, s98, 0x16000
	v_mfma_f32_32x32x16_bf16 v[16:31], v[196:199], v[210:213], v[16:31]
	global_load_lds_dwordx4 v[162:163], off
	v_mfma_f32_32x32x16_bf16 v[0:15], v[196:199], v[214:217], v[0:15]
	v_lshl_add_u64 v[164:165], v[164:165], 0, 64
	v_lshl_add_u64 v[160:161], v[160:161], 0, 64
	v_lshl_add_u64 v[166:167], v[166:167], 0, 64
	v_lshl_add_u64 v[162:163], v[162:163], 0, 64
	s_waitcnt lgkmcnt(0)
	v_mfma_f32_32x32x16_bf16 v[112:127], v[128:131], v[136:139], v[112:127]
	v_mfma_f32_32x32x16_bf16 v[96:111], v[128:131], v[140:143], v[96:111]
	ds_read_b128 v[192:195], v253 offset:32768
	ds_read_b128 v[196:199], v253 offset:34816
	v_mfma_f32_32x32x16_bf16 v[80:95], v[128:131], v[144:147], v[80:95]
	ds_read_b128 v[200:203], v255 offset:49152
	ds_read_b128 v[206:209], v255 offset:51200
	v_mfma_f32_32x32x16_bf16 v[64:79], v[128:131], v[148:151], v[64:79]
	ds_read_b128 v[210:213], v255 offset:53248
	ds_read_b128 v[214:217], v255 offset:55296
	v_mfma_f32_32x32x16_bf16 v[48:63], v[132:135], v[136:139], v[48:63]
	v_mfma_f32_32x32x16_bf16 v[32:47], v[132:135], v[140:143], v[32:47]
	v_mfma_f32_32x32x16_bf16 v[16:31], v[132:135], v[144:147], v[16:31]
	v_mfma_f32_32x32x16_bf16 v[0:15], v[132:135], v[148:151], v[0:15]
	v_xor_b32_e32 v253, 0x10000, v253
	v_xor_b32_e32 v255, 0x10000, v255
	s_waitcnt vmcnt(8)
	s_waitcnt lgkmcnt(0)
	s_mov_b32 s99, 6

; #define LGKM0_BAR asm volatile("s_waitcnt lgkmcnt(0)\n\ts_barrier" ::: "memory");
; __device__ __forceinline__ void gemm256_tile(const u16* Ab, int lda, const u16* Bb, int ldb, int K, char* smem,
;                                              f32x16 (&acc)[2][4]) {
;     ...
;   const int xsw = (lane >> 2) & 3, hh = lane >> 5;
;   const unsigned fo0 = (unsigned)((hh ^ xsw) * 16), fo1 = (unsigned)(((2 + hh) ^ xsw) * 16);
;   const unsigned fa = (unsigned)((wm * 64 + (lane & 31)) * 64);
;   const unsigned fb = (unsigned)(16384 + (wn * 128 + (lane & 31)) * 64);
;     ...
;   asm volatile("s_waitcnt vmcnt(0)" ::: "memory");
;   const bool h1 = __builtin_amdgcn_readfirstlane(wid) >= 4;
;     ...
;   DMA_STAGE(0)
;   if (nks > 1) DMA_STAGE(1)
;   if (nks > 2) DMA_STAGE(2)
;   if (nks > 3) DMA_STAGE(3)
;   if (nks > 3)      asm volatile("s_waitcnt vmcnt(12)\n\ts_barrier" ::: "memory");
;   else if (nks > 2) asm volatile("s_waitcnt vmcnt(8)\n\ts_barrier" ::: "memory");
;   else if (nks > 1) asm volatile("s_waitcnt vmcnt(4)\n\ts_barrier" ::: "memory");
;   else              asm volatile("s_waitcnt vmcnt(0)\n\ts_barrier" ::: "memory");
;   bf16x8 afA[2], bfA[4], afB[2], bfB[4];
;   if (!h1) {
;     G_FRAGS(afA, bfA, 0, fo0)
;     LGKM0_BAR
;     for (int s = 0; s < nks; ++s) {
;       const int q = s & 3;
;       G_MMA(afA, bfA)
;       __builtin_amdgcn_sched_barrier(0);
;       LGKM0_BAR
;       G_FRAGS(afB, bfB, q, fo1)
;       __builtin_amdgcn_sched_barrier(0);
;       LGKM0_BAR
;       G_MMA(afB, bfB)
;       __builtin_amdgcn_sched_barrier(0);
;       G_WAIT_BAR(s)
;       if (s + 4 < nks) DMA_STAGE(s + 4)
;       if (s + 1 < nks) G_FRAGS(afA, bfA, (s + 1) & 3, fo0)
;       __builtin_amdgcn_sched_barrier(0);
;       LGKM0_BAR
;     }
.LBB0_1041:
	v_lshrrev_b32_e32 v192, 6, v152
	v_bfe_u32 v193, v152, 2, 2
	v_readfirstlane_b32 s98, v192
	v_bfe_u32 v194, v152, 5, 1
	v_xor_b32_e32 v193, v194, v193
	v_lshlrev_b32_e32 v193, 4, v193
	v_xor_b32_e32 v194, 32, v193
	v_and_b32_e32 v195, 31, v152
	v_lshrrev_b32_e32 v196, 7, v152
	v_lshl_add_u32 v196, v196, 6, v195
	v_lshlrev_b32_e32 v196, 6, v196
	v_bfe_u32 v197, v152, 6, 1
	v_lshl_add_u32 v197, v197, 7, v195
	v_lshlrev_b32_e32 v197, 6, v197
	v_add3_u32 v154, v196, v193, 16
	v_add3_u32 v253, v196, v194, 16
	v_add3_u32 v254, v197, v193, 16
	v_add3_u32 v255, v197, v194, 16
	s_lshl_b32 s98, s98, 10
	s_add_u32 s98, s98, 16
	v_lshl_add_u64 v[164:165], 64, 2, v[164:165]
	v_lshl_add_u64 v[160:161], 64, 2, v[160:161]
	v_lshl_add_u64 v[166:167], 64, 2, v[166:167]
	v_lshl_add_u64 v[162:163], 64, 2, v[162:163]
	ds_read_b128 v[128:131], v154
	ds_read_b128 v[132:135], v154 offset:2048
	ds_read_b128 v[136:139], v254 offset:16384
	ds_read_b128 v[140:143], v254 offset:18432
	ds_read_b128 v[144:147], v254 offset:20480
	ds_read_b128 v[148:151], v254 offset:22528
	s_waitcnt lgkmcnt(0)
	v_mfma_f32_32x32x16_bf16 v[96:111], v[128:131], v[136:139], 0
	v_mfma_f32_32x32x16_bf16 v[112:127], v[128:131], v[140:143], 0
	ds_read_b128 v[192:195], v253
	ds_read_b128 v[196:199], v253 offset:2048
	v_mfma_f32_32x32x16_bf16 v[64:79], v[128:131], v[144:147], 0
	ds_read_b128 v[200:203], v255 offset:16384
	ds_read_b128 v[206:209], v255 offset:18432
	v_mfma_f32_32x32x16_bf16 v[80:95], v[128:131], v[148:151], 0
	ds_read_b128 v[210:213], v255 offset:20480
	ds_read_b128 v[214:217], v255 offset:22528
	v_mfma_f32_32x32x16_bf16 v[32:47], v[132:135], v[136:139], 0
	v_mfma_f32_32x32x16_bf16 v[48:63], v[132:135], v[140:143], 0
	v_mfma_f32_32x32x16_bf16 v[0:15], v[132:135], v[144:147], 0
	v_mfma_f32_32x32x16_bf16 v[16:31], v[132:135], v[148:151], 0
	s_waitcnt vmcnt(8)
	s_waitcnt lgkmcnt(0)
	s_barrier
	ds_read_b128 v[128:131], v154 offset:32768
	ds_read_b128 v[132:135], v154 offset:34816
	ds_read_b128 v[136:139], v254 offset:49152
	ds_read_b128 v[140:143], v254 offset:51200
	ds_read_b128 v[144:147], v254 offset:53248
	ds_read_b128 v[148:151], v254 offset:55296
	v_xor_b32_e32 v154, 0x10000, v154
	v_xor_b32_e32 v254, 0x10000, v254
	s_add_u32 m0, s98, 0x0
	v_mfma_f32_32x32x16_bf16 v[96:111], v[192:195], v[200:203], v[96:111]
	global_load_lds_dwordx4 v[164:165], off
	v_mfma_f32_32x32x16_bf16 v[112:127], v[192:195], v[206:209], v[112:127]
	s_add_u32 m0, s98, 0x2000
	v_mfma_f32_32x32x16_bf16 v[64:79], v[192:195], v[210:213], v[64:79]
	global_load_lds_dwordx4 v[160:161], off
	v_mfma_f32_32x32x16_bf16 v[80:95], v[192:195], v[214:217], v[80:95]
	s_add_u32 m0, s98, 0x4000
	v_mfma_f32_32x32x16_bf16 v[32:47], v[196:199], v[200:203], v[32:47]
	global_load_lds_dwordx4 v[166:167], off
	v_mfma_f32_32x32x16_bf16 v[48:63], v[196:199], v[206:209], v[48:63]
	s_add_u32 m0, s98, 0x6000
	v_mfma_f32_32x32x16_bf16 v[0:15], v[196:199], v[210:213], v[0:15]
	global_load_lds_dwordx4 v[162:163], off
	v_mfma_f32_32x32x16_bf16 v[16:31], v[196:199], v[214:217], v[16:31]
	v_lshl_add_u64 v[164:165], v[164:165], 0, 64
	v_lshl_add_u64 v[160:161], v[160:161], 0, 64
	v_lshl_add_u64 v[166:167], v[166:167], 0, 64
	v_lshl_add_u64 v[162:163], v[162:163], 0, 64
	s_waitcnt lgkmcnt(0)
	v_mfma_f32_32x32x16_bf16 v[96:111], v[128:131], v[136:139], v[96:111]
	v_mfma_f32_32x32x16_bf16 v[112:127], v[128:131], v[140:143], v[112:127]
	ds_read_b128 v[192:195], v253 offset:32768
	ds_read_b128 v[196:199], v253 offset:34816
	v_mfma_f32_32x32x16_bf16 v[64:79], v[128:131], v[144:147], v[64:79]
	ds_read_b128 v[200:203], v255 offset:49152
	ds_read_b128 v[206:209], v255 offset:51200
	v_mfma_f32_32x32x16_bf16 v[80:95], v[128:131], v[148:151], v[80:95]
	ds_read_b128 v[210:213], v255 offset:53248
	ds_read_b128 v[214:217], v255 offset:55296
	v_mfma_f32_32x32x16_bf16 v[32:47], v[132:135], v[136:139], v[32:47]
	v_mfma_f32_32x32x16_bf16 v[48:63], v[132:135], v[140:143], v[48:63]
	v_mfma_f32_32x32x16_bf16 v[0:15], v[132:135], v[144:147], v[0:15]
	v_mfma_f32_32x32x16_bf16 v[16:31], v[132:135], v[148:151], v[16:31]
	v_xor_b32_e32 v253, 0x10000, v253
	v_xor_b32_e32 v255, 0x10000, v255
	s_waitcnt vmcnt(8)
	s_waitcnt lgkmcnt(0)
	s_barrier
; #define LGKM0_BAR asm volatile("s_waitcnt lgkmcnt(0)\n\ts_barrier" ::: "memory");
; __device__ __forceinline__ void gemm256_tile(const u16* Ab, int lda, const u16* Bb, int ldb, int K, char* smem,
;                                              f32x16 (&acc)[2][4]) {
;     ...
;     for (int s = 0; s < nks; ++s) {
;       const int q = s & 3;
;       G_MMA(afA, bfA)
;       __builtin_amdgcn_sched_barrier(0);
;       LGKM0_BAR
;       G_FRAGS(afB, bfB, q, fo1)
;       __builtin_amdgcn_sched_barrier(0);
;       LGKM0_BAR
;       G_MMA(afB, bfB)
;       __builtin_amdgcn_sched_barrier(0);
;       G_WAIT_BAR(s)
;       if (s + 4 < nks) DMA_STAGE(s + 4)
;       if (s + 1 < nks) G_FRAGS(afA, bfA, (s + 1) & 3, fo0)
;       __builtin_amdgcn_sched_barrier(0);
;       LGKM0_BAR
;     }
	ds_read_b128 v[128:131], v154
	ds_read_b128 v[132:135], v154 offset:2048
	ds_read_b128 v[136:139], v254 offset:16384
	ds_read_b128 v[140:143], v254 offset:18432
	ds_read_b128 v[144:147], v254 offset:20480
	ds_read_b128 v[148:151], v254 offset:22528
	s_add_u32 m0, s98, 0x8000
	v_mfma_f32_32x32x16_bf16 v[96:111], v[192:195], v[200:203], v[96:111]
	global_load_lds_dwordx4 v[164:165], off
	v_mfma_f32_32x32x16_bf16 v[112:127], v[192:195], v[206:209], v[112:127]
	s_add_u32 m0, s98, 0xa000
	v_mfma_f32_32x32x16_bf16 v[64:79], v[192:195], v[210:213], v[64:79]
	global_load_lds_dwordx4 v[160:161], off
	v_mfma_f32_32x32x16_bf16 v[80:95], v[192:195], v[214:217], v[80:95]
	s_add_u32 m0, s98, 0xc000
	v_mfma_f32_32x32x16_bf16 v[32:47], v[196:199], v[200:203], v[32:47]
	global_load_lds_dwordx4 v[166:167], off
	v_mfma_f32_32x32x16_bf16 v[48:63], v[196:199], v[206:209], v[48:63]
	s_add_u32 m0, s98, 0xe000
	v_mfma_f32_32x32x16_bf16 v[0:15], v[196:199], v[210:213], v[0:15]
	global_load_lds_dwordx4 v[162:163], off
	v_mfma_f32_32x32x16_bf16 v[16:31], v[196:199], v[214:217], v[16:31]
	v_lshl_add_u64 v[164:165], v[164:165], 0, 64
	v_lshl_add_u64 v[160:161], v[160:161], 0, 64
	v_lshl_add_u64 v[166:167], v[166:167], 0, 64
	v_lshl_add_u64 v[162:163], v[162:163], 0, 64
	s_waitcnt lgkmcnt(0)
	v_mfma_f32_32x32x16_bf16 v[96:111], v[128:131], v[136:139], v[96:111]
	v_mfma_f32_32x32x16_bf16 v[112:127], v[128:131], v[140:143], v[112:127]
	ds_read_b128 v[192:195], v253
	ds_read_b128 v[196:199], v253 offset:2048
	v_mfma_f32_32x32x16_bf16 v[64:79], v[128:131], v[144:147], v[64:79]
	ds_read_b128 v[200:203], v255 offset:16384
	ds_read_b128 v[206:209], v255 offset:18432
	v_mfma_f32_32x32x16_bf16 v[80:95], v[128:131], v[148:151], v[80:95]
	ds_read_b128 v[210:213], v255 offset:20480
	ds_read_b128 v[214:217], v255 offset:22528
	v_mfma_f32_32x32x16_bf16 v[32:47], v[132:135], v[136:139], v[32:47]
	v_mfma_f32_32x32x16_bf16 v[48:63], v[132:135], v[140:143], v[48:63]
	v_mfma_f32_32x32x16_bf16 v[0:15], v[132:135], v[144:147], v[0:15]
	v_mfma_f32_32x32x16_bf16 v[16:31], v[132:135], v[148:151], v[16:31]
	s_waitcnt vmcnt(8)
	s_waitcnt lgkmcnt(0)
	s_barrier
	ds_read_b128 v[128:131], v154 offset:32768
	ds_read_b128 v[132:135], v154 offset:34816
	ds_read_b128 v[136:139], v254 offset:49152
	ds_read_b128 v[140:143], v254 offset:51200
	ds_read_b128 v[144:147], v254 offset:53248
	ds_read_b128 v[148:151], v254 offset:55296
	v_xor_b32_e32 v154, 0x10000, v154
	v_xor_b32_e32 v254, 0x10000, v254
	s_add_u32 m0, s98, 0x10000
	v_mfma_f32_32x32x16_bf16 v[96:111], v[192:195], v[200:203], v[96:111]
	global_load_lds_dwordx4 v[164:165], off
	v_mfma_f32_32x32x16_bf16 v[112:127], v[192:195], v[206:209], v[112:127]
	s_add_u32 m0, s98, 0x12000
	v_mfma_f32_32x32x16_bf16 v[64:79], v[192:195], v[210:213], v[64:79]
	global_load_lds_dwordx4 v[160:161], off
	v_mfma_f32_32x32x16_bf16 v[80:95], v[192:195], v[214:217], v[80:95]
	s_add_u32 m0, s98, 0x14000
	v_mfma_f32_32x32x16_bf16 v[32:47], v[196:199], v[200:203], v[32:47]
	global_load_lds_dwordx4 v[166:167], off
	v_mfma_f32_32x32x16_bf16 v[48:63], v[196:199], v[206:209], v[48:63]
	s_add_u32 m0, s98, 0x16000
	v_mfma_f32_32x32x16_bf16 v[0:15], v[196:199], v[210:213], v[0:15]
	global_load_lds_dwordx4 v[162:163], off
	v_mfma_f32_32x32x16_bf16 v[16:31], v[196:199], v[214:217], v[16:31]
	v_lshl_add_u64 v[164:165], v[164:165], 0, 64
	v_lshl_add_u64 v[160:161], v[160:161], 0, 64
	v_lshl_add_u64 v[166:167], v[166:167], 0, 64
	v_lshl_add_u64 v[162:163], v[162:163], 0, 64
	s_waitcnt lgkmcnt(0)
	v_mfma_f32_32x32x16_bf16 v[96:111], v[128:131], v[136:139], v[96:111]
	v_mfma_f32_32x32x16_bf16 v[112:127], v[128:131], v[140:143], v[112:127]
	ds_read_b128 v[192:195], v253 offset:32768
	ds_read_b128 v[196:199], v253 offset:34816
	v_mfma_f32_32x32x16_bf16 v[64:79], v[128:131], v[144:147], v[64:79]
	ds_read_b128 v[200:203], v255 offset:49152
	ds_read_b128 v[206:209], v255 offset:51200
	v_mfma_f32_32x32x16_bf16 v[80:95], v[128:131], v[148:151], v[80:95]
	ds_read_b128 v[210:213], v255 offset:53248
	ds_read_b128 v[214:217], v255 offset:55296
	v_mfma_f32_32x32x16_bf16 v[32:47], v[132:135], v[136:139], v[32:47]
	v_mfma_f32_32x32x16_bf16 v[48:63], v[132:135], v[140:143], v[48:63]
	v_mfma_f32_32x32x16_bf16 v[0:15], v[132:135], v[144:147], v[0:15]
	v_mfma_f32_32x32x16_bf16 v[16:31], v[132:135], v[148:151], v[16:31]
	v_xor_b32_e32 v253, 0x10000, v253
	v_xor_b32_e32 v255, 0x10000, v255
	s_waitcnt vmcnt(8)
	s_waitcnt lgkmcnt(0)
	s_mov_b32 s99, 6

; #define LGKM0_BAR asm volatile("s_waitcnt lgkmcnt(0)\n\ts_barrier" ::: "memory");
; __device__ __forceinline__ void gemm256_tile(const u16* Ab, int lda, const u16* Bb, int ldb, int K, char* smem,
;                                              f32x16 (&acc)[2][4]) {
;     ...
;   const int xsw = (lane >> 2) & 3, hh = lane >> 5;
;   const unsigned fo0 = (unsigned)((hh ^ xsw) * 16), fo1 = (unsigned)(((2 + hh) ^ xsw) * 16);
;   const unsigned fa = (unsigned)((wm * 64 + (lane & 31)) * 64);
;   const unsigned fb = (unsigned)(16384 + (wn * 128 + (lane & 31)) * 64);
;     ...
;   asm volatile("s_waitcnt vmcnt(0)" ::: "memory");
;   const bool h1 = __builtin_amdgcn_readfirstlane(wid) >= 4;
;     ...
;   DMA_STAGE(0)
;   if (nks > 1) DMA_STAGE(1)
;   if (nks > 2) DMA_STAGE(2)
;   if (nks > 3) DMA_STAGE(3)
;   if (nks > 3)      asm volatile("s_waitcnt vmcnt(12)\n\ts_barrier" ::: "memory");
;   else if (nks > 2) asm volatile("s_waitcnt vmcnt(8)\n\ts_barrier" ::: "memory");
;   else if (nks > 1) asm volatile("s_waitcnt vmcnt(4)\n\ts_barrier" ::: "memory");
;   else              asm volatile("s_waitcnt vmcnt(0)\n\ts_barrier" ::: "memory");
;   bf16x8 afA[2], bfA[4], afB[2], bfB[4];
;   if (!h1) {
;     G_FRAGS(afA, bfA, 0, fo0)
;     LGKM0_BAR
;     for (int s = 0; s < nks; ++s) {
;       const int q = s & 3;
;       G_MMA(afA, bfA)
;       __builtin_amdgcn_sched_barrier(0);
;       LGKM0_BAR
;       G_FRAGS(afB, bfB, q, fo1)
;       __builtin_amdgcn_sched_barrier(0);
;       LGKM0_BAR
;       G_MMA(afB, bfB)
;       __builtin_amdgcn_sched_barrier(0);
;       G_WAIT_BAR(s)
;       if (s + 4 < nks) DMA_STAGE(s + 4)
;       if (s + 1 < nks) G_FRAGS(afA, bfA, (s + 1) & 3, fo0)
;       __builtin_amdgcn_sched_barrier(0);
;       LGKM0_BAR
;     }
.LBB0_1161:
	v_lshrrev_b32_e32 v192, 6, v152
	v_bfe_u32 v193, v152, 2, 2
	v_readfirstlane_b32 s98, v192
	v_bfe_u32 v194, v152, 5, 1
	v_xor_b32_e32 v193, v194, v193
	v_lshlrev_b32_e32 v193, 4, v193
	v_xor_b32_e32 v194, 32, v193
	v_and_b32_e32 v195, 31, v152
	v_lshrrev_b32_e32 v196, 7, v152
	v_lshl_add_u32 v196, v196, 6, v195
	v_lshlrev_b32_e32 v196, 6, v196
	v_bfe_u32 v197, v152, 6, 1
	v_lshl_add_u32 v197, v197, 7, v195
	v_lshlrev_b32_e32 v197, 6, v197
	v_add3_u32 v154, v196, v193, 16
	v_add3_u32 v253, v196, v194, 16
	v_add3_u32 v254, v197, v193, 16
	v_add3_u32 v255, v197, v194, 16
	s_lshl_b32 s98, s98, 10
	s_add_u32 s98, s98, 16
	v_lshl_add_u64 v[160:161], 64, 2, v[160:161]
	v_lshl_add_u64 v[162:163], 64, 2, v[162:163]
	v_lshl_add_u64 v[164:165], 64, 2, v[164:165]
	v_lshl_add_u64 v[166:167], 64, 2, v[166:167]
	ds_read_b128 v[128:131], v154
	ds_read_b128 v[132:135], v154 offset:2048
	ds_read_b128 v[136:139], v254 offset:16384
	ds_read_b128 v[140:143], v254 offset:18432
	ds_read_b128 v[144:147], v254 offset:20480
	ds_read_b128 v[148:151], v254 offset:22528
	s_waitcnt lgkmcnt(0)
	v_mfma_f32_32x32x16_bf16 v[112:127], v[128:131], v[136:139], 0
	v_mfma_f32_32x32x16_bf16 v[96:111], v[128:131], v[140:143], 0
	ds_read_b128 v[192:195], v253
	ds_read_b128 v[196:199], v253 offset:2048
	v_mfma_f32_32x32x16_bf16 v[80:95], v[128:131], v[144:147], 0
	ds_read_b128 v[200:203], v255 offset:16384
	ds_read_b128 v[206:209], v255 offset:18432
	v_mfma_f32_32x32x16_bf16 v[64:79], v[128:131], v[148:151], 0
	ds_read_b128 v[210:213], v255 offset:20480
	ds_read_b128 v[214:217], v255 offset:22528
	v_mfma_f32_32x32x16_bf16 v[48:63], v[132:135], v[136:139], 0
	v_mfma_f32_32x32x16_bf16 v[32:47], v[132:135], v[140:143], 0
	v_mfma_f32_32x32x16_bf16 v[16:31], v[132:135], v[144:147], 0
	v_mfma_f32_32x32x16_bf16 v[0:15], v[132:135], v[148:151], 0
	s_waitcnt vmcnt(8)
	s_waitcnt lgkmcnt(0)
	s_barrier
	ds_read_b128 v[128:131], v154 offset:32768
	ds_read_b128 v[132:135], v154 offset:34816
	ds_read_b128 v[136:139], v254 offset:49152
	ds_read_b128 v[140:143], v254 offset:51200
	ds_read_b128 v[144:147], v254 offset:53248
	ds_read_b128 v[148:151], v254 offset:55296
	v_xor_b32_e32 v154, 0x10000, v154
	v_xor_b32_e32 v254, 0x10000, v254
	s_add_u32 m0, s98, 0x0
	v_mfma_f32_32x32x16_bf16 v[112:127], v[192:195], v[200:203], v[112:127]
	global_load_lds_dwordx4 v[160:161], off
	v_mfma_f32_32x32x16_bf16 v[96:111], v[192:195], v[206:209], v[96:111]
	s_add_u32 m0, s98, 0x2000
	v_mfma_f32_32x32x16_bf16 v[80:95], v[192:195], v[210:213], v[80:95]
	global_load_lds_dwordx4 v[162:163], off
	v_mfma_f32_32x32x16_bf16 v[64:79], v[192:195], v[214:217], v[64:79]
	s_add_u32 m0, s98, 0x4000
	v_mfma_f32_32x32x16_bf16 v[48:63], v[196:199], v[200:203], v[48:63]
	global_load_lds_dwordx4 v[164:165], off
	v_mfma_f32_32x32x16_bf16 v[32:47], v[196:199], v[206:209], v[32:47]
	s_add_u32 m0, s98, 0x6000
	v_mfma_f32_32x32x16_bf16 v[16:31], v[196:199], v[210:213], v[16:31]
	global_load_lds_dwordx4 v[166:167], off
	v_mfma_f32_32x32x16_bf16 v[0:15], v[196:199], v[214:217], v[0:15]
	v_lshl_add_u64 v[160:161], v[160:161], 0, 64
	v_lshl_add_u64 v[162:163], v[162:163], 0, 64
	v_lshl_add_u64 v[164:165], v[164:165], 0, 64
	v_lshl_add_u64 v[166:167], v[166:167], 0, 64
	s_waitcnt lgkmcnt(0)
	v_mfma_f32_32x32x16_bf16 v[112:127], v[128:131], v[136:139], v[112:127]
	v_mfma_f32_32x32x16_bf16 v[96:111], v[128:131], v[140:143], v[96:111]
	ds_read_b128 v[192:195], v253 offset:32768
	ds_read_b128 v[196:199], v253 offset:34816
	v_mfma_f32_32x32x16_bf16 v[80:95], v[128:131], v[144:147], v[80:95]
	ds_read_b128 v[200:203], v255 offset:49152
	ds_read_b128 v[206:209], v255 offset:51200
	v_mfma_f32_32x32x16_bf16 v[64:79], v[128:131], v[148:151], v[64:79]
	ds_read_b128 v[210:213], v255 offset:53248
	ds_read_b128 v[214:217], v255 offset:55296
	v_mfma_f32_32x32x16_bf16 v[48:63], v[132:135], v[136:139], v[48:63]
	v_mfma_f32_32x32x16_bf16 v[32:47], v[132:135], v[140:143], v[32:47]
	v_mfma_f32_32x32x16_bf16 v[16:31], v[132:135], v[144:147], v[16:31]
	v_mfma_f32_32x32x16_bf16 v[0:15], v[132:135], v[148:151], v[0:15]
	v_xor_b32_e32 v253, 0x10000, v253
	v_xor_b32_e32 v255, 0x10000, v255
	s_waitcnt vmcnt(8)
	s_waitcnt lgkmcnt(0)
	s_barrier
; #define LGKM0_BAR asm volatile("s_waitcnt lgkmcnt(0)\n\ts_barrier" ::: "memory");
; __device__ __forceinline__ void gemm256_tile(const u16* Ab, int lda, const u16* Bb, int ldb, int K, char* smem,
;                                              f32x16 (&acc)[2][4]) {
;     ...
;     for (int s = 0; s < nks; ++s) {
;       const int q = s & 3;
;       G_MMA(afA, bfA)
;       __builtin_amdgcn_sched_barrier(0);
;       LGKM0_BAR
;       G_FRAGS(afB, bfB, q, fo1)
;       __builtin_amdgcn_sched_barrier(0);
;       LGKM0_BAR
;       G_MMA(afB, bfB)
;       __builtin_amdgcn_sched_barrier(0);
;       G_WAIT_BAR(s)
;       if (s + 4 < nks) DMA_STAGE(s + 4)
;       if (s + 1 < nks) G_FRAGS(afA, bfA, (s + 1) & 3, fo0)
;       __builtin_amdgcn_sched_barrier(0);
;       LGKM0_BAR
;     }
	ds_read_b128 v[128:131], v154
	ds_read_b128 v[132:135], v154 offset:2048
	ds_read_b128 v[136:139], v254 offset:16384
	ds_read_b128 v[140:143], v254 offset:18432
	ds_read_b128 v[144:147], v254 offset:20480
	ds_read_b128 v[148:151], v254 offset:22528
	s_add_u32 m0, s98, 0x8000
	v_mfma_f32_32x32x16_bf16 v[112:127], v[192:195], v[200:203], v[112:127]
	global_load_lds_dwordx4 v[160:161], off
	v_mfma_f32_32x32x16_bf16 v[96:111], v[192:195], v[206:209], v[96:111]
	s_add_u32 m0, s98, 0xa000
	v_mfma_f32_32x32x16_bf16 v[80:95], v[192:195], v[210:213], v[80:95]
	global_load_lds_dwordx4 v[162:163], off
	v_mfma_f32_32x32x16_bf16 v[64:79], v[192:195], v[214:217], v[64:79]
	s_add_u32 m0, s98, 0xc000
	v_mfma_f32_32x32x16_bf16 v[48:63], v[196:199], v[200:203], v[48:63]
	global_load_lds_dwordx4 v[164:165], off
	v_mfma_f32_32x32x16_bf16 v[32:47], v[196:199], v[206:209], v[32:47]
	s_add_u32 m0, s98, 0xe000
	v_mfma_f32_32x32x16_bf16 v[16:31], v[196:199], v[210:213], v[16:31]
	global_load_lds_dwordx4 v[166:167], off
	v_mfma_f32_32x32x16_bf16 v[0:15], v[196:199], v[214:217], v[0:15]
	v_lshl_add_u64 v[160:161], v[160:161], 0, 64
	v_lshl_add_u64 v[162:163], v[162:163], 0, 64
	v_lshl_add_u64 v[164:165], v[164:165], 0, 64
	v_lshl_add_u64 v[166:167], v[166:167], 0, 64
	s_waitcnt lgkmcnt(0)
	v_mfma_f32_32x32x16_bf16 v[112:127], v[128:131], v[136:139], v[112:127]
	v_mfma_f32_32x32x16_bf16 v[96:111], v[128:131], v[140:143], v[96:111]
	ds_read_b128 v[192:195], v253
	ds_read_b128 v[196:199], v253 offset:2048
	v_mfma_f32_32x32x16_bf16 v[80:95], v[128:131], v[144:147], v[80:95]
	ds_read_b128 v[200:203], v255 offset:16384
	ds_read_b128 v[206:209], v255 offset:18432
	v_mfma_f32_32x32x16_bf16 v[64:79], v[128:131], v[148:151], v[64:79]
	ds_read_b128 v[210:213], v255 offset:20480
	ds_read_b128 v[214:217], v255 offset:22528
	v_mfma_f32_32x32x16_bf16 v[48:63], v[132:135], v[136:139], v[48:63]
	v_mfma_f32_32x32x16_bf16 v[32:47], v[132:135], v[140:143], v[32:47]
	v_mfma_f32_32x32x16_bf16 v[16:31], v[132:135], v[144:147], v[16:31]
	v_mfma_f32_32x32x16_bf16 v[0:15], v[132:135], v[148:151], v[0:15]
	s_waitcnt vmcnt(8)
	s_waitcnt lgkmcnt(0)
	s_barrier
	ds_read_b128 v[128:131], v154 offset:32768
	ds_read_b128 v[132:135], v154 offset:34816
	ds_read_b128 v[136:139], v254 offset:49152
	ds_read_b128 v[140:143], v254 offset:51200
	ds_read_b128 v[144:147], v254 offset:53248
	ds_read_b128 v[148:151], v254 offset:55296
	v_xor_b32_e32 v154, 0x10000, v154
	v_xor_b32_e32 v254, 0x10000, v254
	s_add_u32 m0, s98, 0x10000
	v_mfma_f32_32x32x16_bf16 v[112:127], v[192:195], v[200:203], v[112:127]
	global_load_lds_dwordx4 v[160:161], off
	v_mfma_f32_32x32x16_bf16 v[96:111], v[192:195], v[206:209], v[96:111]
	s_add_u32 m0, s98, 0x12000
	v_mfma_f32_32x32x16_bf16 v[80:95], v[192:195], v[210:213], v[80:95]
	global_load_lds_dwordx4 v[162:163], off
	v_mfma_f32_32x32x16_bf16 v[64:79], v[192:195], v[214:217], v[64:79]
	s_add_u32 m0, s98, 0x14000
	v_mfma_f32_32x32x16_bf16 v[48:63], v[196:199], v[200:203], v[48:63]
	global_load_lds_dwordx4 v[164:165], off
	v_mfma_f32_32x32x16_bf16 v[32:47], v[196:199], v[206:209], v[32:47]
	s_add_u32 m0, s98, 0x16000
	v_mfma_f32_32x32x16_bf16 v[16:31], v[196:199], v[210:213], v[16:31]
	global_load_lds_dwordx4 v[166:167], off
	v_mfma_f32_32x32x16_bf16 v[0:15], v[196:199], v[214:217], v[0:15]
	v_lshl_add_u64 v[160:161], v[160:161], 0, 64
	v_lshl_add_u64 v[162:163], v[162:163], 0, 64
	v_lshl_add_u64 v[164:165], v[164:165], 0, 64
	v_lshl_add_u64 v[166:167], v[166:167], 0, 64
	s_waitcnt lgkmcnt(0)
	v_mfma_f32_32x32x16_bf16 v[112:127], v[128:131], v[136:139], v[112:127]
	v_mfma_f32_32x32x16_bf16 v[96:111], v[128:131], v[140:143], v[96:111]
	ds_read_b128 v[192:195], v253 offset:32768
	ds_read_b128 v[196:199], v253 offset:34816
	v_mfma_f32_32x32x16_bf16 v[80:95], v[128:131], v[144:147], v[80:95]
	ds_read_b128 v[200:203], v255 offset:49152
	ds_read_b128 v[206:209], v255 offset:51200
	v_mfma_f32_32x32x16_bf16 v[64:79], v[128:131], v[148:151], v[64:79]
	ds_read_b128 v[210:213], v255 offset:53248
	ds_read_b128 v[214:217], v255 offset:55296
	v_mfma_f32_32x32x16_bf16 v[48:63], v[132:135], v[136:139], v[48:63]
	v_mfma_f32_32x32x16_bf16 v[32:47], v[132:135], v[140:143], v[32:47]
	v_mfma_f32_32x32x16_bf16 v[16:31], v[132:135], v[144:147], v[16:31]
	v_mfma_f32_32x32x16_bf16 v[0:15], v[132:135], v[148:151], v[0:15]
	v_xor_b32_e32 v253, 0x10000, v253
	v_xor_b32_e32 v255, 0x10000, v255
	s_waitcnt vmcnt(8)
	s_waitcnt lgkmcnt(0)
	s_mov_b32 s99, 20

; #define LGKM0_BAR asm volatile("s_waitcnt lgkmcnt(0)\n\ts_barrier" ::: "memory");
; __device__ __forceinline__ void gemm256_tile(const u16* Ab, int lda, const u16* Bb, int ldb, int K, char* smem,
;                                              f32x16 (&acc)[2][4]) {
;     ...
;   const int xsw = (lane >> 2) & 3, hh = lane >> 5;
;   const unsigned fo0 = (unsigned)((hh ^ xsw) * 16), fo1 = (unsigned)(((2 + hh) ^ xsw) * 16);
;   const unsigned fa = (unsigned)((wm * 64 + (lane & 31)) * 64);
;   const unsigned fb = (unsigned)(16384 + (wn * 128 + (lane & 31)) * 64);
;     ...
;   asm volatile("s_waitcnt vmcnt(0)" ::: "memory");
;   const bool h1 = __builtin_amdgcn_readfirstlane(wid) >= 4;
;     ...
;   DMA_STAGE(0)
;   if (nks > 1) DMA_STAGE(1)
;   if (nks > 2) DMA_STAGE(2)
;   if (nks > 3) DMA_STAGE(3)
;   if (nks > 3)      asm volatile("s_waitcnt vmcnt(12)\n\ts_barrier" ::: "memory");
;   else if (nks > 2) asm volatile("s_waitcnt vmcnt(8)\n\ts_barrier" ::: "memory");
;   else if (nks > 1) asm volatile("s_waitcnt vmcnt(4)\n\ts_barrier" ::: "memory");
;   else              asm volatile("s_waitcnt vmcnt(0)\n\ts_barrier" ::: "memory");
;   bf16x8 afA[2], bfA[4], afB[2], bfB[4];
;   if (!h1) {
;     G_FRAGS(afA, bfA, 0, fo0)
;     LGKM0_BAR
;     for (int s = 0; s < nks; ++s) {
;       const int q = s & 3;
;       G_MMA(afA, bfA)
;       __builtin_amdgcn_sched_barrier(0);
;       LGKM0_BAR
;       G_FRAGS(afB, bfB, q, fo1)
;       __builtin_amdgcn_sched_barrier(0);
;       LGKM0_BAR
;       G_MMA(afB, bfB)
;       __builtin_amdgcn_sched_barrier(0);
;       G_WAIT_BAR(s)
;       if (s + 4 < nks) DMA_STAGE(s + 4)
;       if (s + 1 < nks) G_FRAGS(afA, bfA, (s + 1) & 3, fo0)
;       __builtin_amdgcn_sched_barrier(0);
;       LGKM0_BAR
;     }
.LBB0_1395:
	v_lshrrev_b32_e32 v194, 6, v152
	v_bfe_u32 v195, v152, 2, 2
	v_readfirstlane_b32 s98, v194
	v_bfe_u32 v196, v152, 5, 1
	v_xor_b32_e32 v195, v196, v195
	v_lshlrev_b32_e32 v195, 4, v195
	v_xor_b32_e32 v196, 32, v195
	v_and_b32_e32 v197, 31, v152
	v_lshrrev_b32_e32 v198, 7, v152
	v_lshl_add_u32 v198, v198, 6, v197
	v_lshlrev_b32_e32 v198, 6, v198
	v_bfe_u32 v199, v152, 6, 1
	v_lshl_add_u32 v199, v199, 7, v197
	v_lshlrev_b32_e32 v199, 6, v199
	v_add3_u32 v154, v198, v195, 16
	v_add3_u32 v193, v198, v196, 16
	v_add3_u32 v202, v199, v195, 16
	v_add3_u32 v203, v199, v196, 16
	s_lshl_b32 s98, s98, 10
	s_add_u32 s98, s98, 16
	v_lshl_add_u64 v[164:165], 64, 2, v[164:165]
	v_lshl_add_u64 v[160:161], 64, 2, v[160:161]
	v_lshl_add_u64 v[166:167], 64, 2, v[166:167]
	v_lshl_add_u64 v[162:163], 64, 2, v[162:163]
	ds_read_b128 v[128:131], v154
	ds_read_b128 v[132:135], v154 offset:2048
	ds_read_b128 v[136:139], v202 offset:16384
	ds_read_b128 v[140:143], v202 offset:18432
	ds_read_b128 v[144:147], v202 offset:20480
	ds_read_b128 v[148:151], v202 offset:22528
	s_waitcnt lgkmcnt(0)
	v_mfma_f32_32x32x16_bf16 v[112:127], v[128:131], v[136:139], 0
	v_mfma_f32_32x32x16_bf16 v[96:111], v[128:131], v[140:143], 0
	ds_read_b128 v[194:197], v193
	ds_read_b128 v[198:201], v193 offset:2048
	v_mfma_f32_32x32x16_bf16 v[80:95], v[128:131], v[144:147], 0
	ds_read_b128 v[206:209], v203 offset:16384
	ds_read_b128 v[210:213], v203 offset:18432
	v_mfma_f32_32x32x16_bf16 v[64:79], v[128:131], v[148:151], 0
	ds_read_b128 v[214:217], v203 offset:20480
	ds_read_b128 v[218:221], v203 offset:22528
	v_mfma_f32_32x32x16_bf16 v[48:63], v[132:135], v[136:139], 0
	v_mfma_f32_32x32x16_bf16 v[32:47], v[132:135], v[140:143], 0
	v_mfma_f32_32x32x16_bf16 v[16:31], v[132:135], v[144:147], 0
	v_mfma_f32_32x32x16_bf16 v[0:15], v[132:135], v[148:151], 0
	s_waitcnt vmcnt(8)
	s_waitcnt lgkmcnt(0)
	s_barrier
	ds_read_b128 v[128:131], v154 offset:32768
	ds_read_b128 v[132:135], v154 offset:34816
	ds_read_b128 v[136:139], v202 offset:49152
	ds_read_b128 v[140:143], v202 offset:51200
	ds_read_b128 v[144:147], v202 offset:53248
	ds_read_b128 v[148:151], v202 offset:55296
	v_xor_b32_e32 v154, 0x10000, v154
	v_xor_b32_e32 v202, 0x10000, v202
	s_add_u32 m0, s98, 0x0
	v_mfma_f32_32x32x16_bf16 v[112:127], v[194:197], v[206:209], v[112:127]
	global_load_lds_dwordx4 v[164:165], off
	v_mfma_f32_32x32x16_bf16 v[96:111], v[194:197], v[210:213], v[96:111]
	s_add_u32 m0, s98, 0x2000
	v_mfma_f32_32x32x16_bf16 v[80:95], v[194:197], v[214:217], v[80:95]
	global_load_lds_dwordx4 v[160:161], off
	v_mfma_f32_32x32x16_bf16 v[64:79], v[194:197], v[218:221], v[64:79]
	s_add_u32 m0, s98, 0x4000
	v_mfma_f32_32x32x16_bf16 v[48:63], v[198:201], v[206:209], v[48:63]
	global_load_lds_dwordx4 v[166:167], off
	v_mfma_f32_32x32x16_bf16 v[32:47], v[198:201], v[210:213], v[32:47]
	s_add_u32 m0, s98, 0x6000
	v_mfma_f32_32x32x16_bf16 v[16:31], v[198:201], v[214:217], v[16:31]
	global_load_lds_dwordx4 v[162:163], off
	v_mfma_f32_32x32x16_bf16 v[0:15], v[198:201], v[218:221], v[0:15]
	v_lshl_add_u64 v[164:165], v[164:165], 0, 64
	v_lshl_add_u64 v[160:161], v[160:161], 0, 64
	v_lshl_add_u64 v[166:167], v[166:167], 0, 64
	v_lshl_add_u64 v[162:163], v[162:163], 0, 64
	s_waitcnt lgkmcnt(0)
	v_mfma_f32_32x32x16_bf16 v[112:127], v[128:131], v[136:139], v[112:127]
	v_mfma_f32_32x32x16_bf16 v[96:111], v[128:131], v[140:143], v[96:111]
	ds_read_b128 v[194:197], v193 offset:32768
	ds_read_b128 v[198:201], v193 offset:34816
	v_mfma_f32_32x32x16_bf16 v[80:95], v[128:131], v[144:147], v[80:95]
	ds_read_b128 v[206:209], v203 offset:49152
	ds_read_b128 v[210:213], v203 offset:51200
	v_mfma_f32_32x32x16_bf16 v[64:79], v[128:131], v[148:151], v[64:79]
	ds_read_b128 v[214:217], v203 offset:53248
	ds_read_b128 v[218:221], v203 offset:55296
	v_mfma_f32_32x32x16_bf16 v[48:63], v[132:135], v[136:139], v[48:63]
	v_mfma_f32_32x32x16_bf16 v[32:47], v[132:135], v[140:143], v[32:47]
	v_mfma_f32_32x32x16_bf16 v[16:31], v[132:135], v[144:147], v[16:31]
	v_mfma_f32_32x32x16_bf16 v[0:15], v[132:135], v[148:151], v[0:15]
	v_xor_b32_e32 v193, 0x10000, v193
	v_xor_b32_e32 v203, 0x10000, v203
	s_waitcnt vmcnt(8)
	s_waitcnt lgkmcnt(0)
	s_barrier
; #define LGKM0_BAR asm volatile("s_waitcnt lgkmcnt(0)\n\ts_barrier" ::: "memory");
; __device__ __forceinline__ void gemm256_tile(const u16* Ab, int lda, const u16* Bb, int ldb, int K, char* smem,
;                                              f32x16 (&acc)[2][4]) {
;     ...
;     for (int s = 0; s < nks; ++s) {
;       const int q = s & 3;
;       G_MMA(afA, bfA)
;       __builtin_amdgcn_sched_barrier(0);
;       LGKM0_BAR
;       G_FRAGS(afB, bfB, q, fo1)
;       __builtin_amdgcn_sched_barrier(0);
;       LGKM0_BAR
;       G_MMA(afB, bfB)
;       __builtin_amdgcn_sched_barrier(0);
;       G_WAIT_BAR(s)
;       if (s + 4 < nks) DMA_STAGE(s + 4)
;       if (s + 1 < nks) G_FRAGS(afA, bfA, (s + 1) & 3, fo0)
;       __builtin_amdgcn_sched_barrier(0);
;       LGKM0_BAR
;     }
	ds_read_b128 v[128:131], v154
	ds_read_b128 v[132:135], v154 offset:2048
	ds_read_b128 v[136:139], v202 offset:16384
	ds_read_b128 v[140:143], v202 offset:18432
	ds_read_b128 v[144:147], v202 offset:20480
	ds_read_b128 v[148:151], v202 offset:22528
	s_add_u32 m0, s98, 0x8000
	v_mfma_f32_32x32x16_bf16 v[112:127], v[194:197], v[206:209], v[112:127]
	global_load_lds_dwordx4 v[164:165], off
	v_mfma_f32_32x32x16_bf16 v[96:111], v[194:197], v[210:213], v[96:111]
	s_add_u32 m0, s98, 0xa000
	v_mfma_f32_32x32x16_bf16 v[80:95], v[194:197], v[214:217], v[80:95]
	global_load_lds_dwordx4 v[160:161], off
	v_mfma_f32_32x32x16_bf16 v[64:79], v[194:197], v[218:221], v[64:79]
	s_add_u32 m0, s98, 0xc000
	v_mfma_f32_32x32x16_bf16 v[48:63], v[198:201], v[206:209], v[48:63]
	global_load_lds_dwordx4 v[166:167], off
	v_mfma_f32_32x32x16_bf16 v[32:47], v[198:201], v[210:213], v[32:47]
	s_add_u32 m0, s98, 0xe000
	v_mfma_f32_32x32x16_bf16 v[16:31], v[198:201], v[214:217], v[16:31]
	global_load_lds_dwordx4 v[162:163], off
	v_mfma_f32_32x32x16_bf16 v[0:15], v[198:201], v[218:221], v[0:15]
	v_lshl_add_u64 v[164:165], v[164:165], 0, 64
	v_lshl_add_u64 v[160:161], v[160:161], 0, 64
	v_lshl_add_u64 v[166:167], v[166:167], 0, 64
	v_lshl_add_u64 v[162:163], v[162:163], 0, 64
	s_waitcnt lgkmcnt(0)
	v_mfma_f32_32x32x16_bf16 v[112:127], v[128:131], v[136:139], v[112:127]
	v_mfma_f32_32x32x16_bf16 v[96:111], v[128:131], v[140:143], v[96:111]
	ds_read_b128 v[194:197], v193
	ds_read_b128 v[198:201], v193 offset:2048
	v_mfma_f32_32x32x16_bf16 v[80:95], v[128:131], v[144:147], v[80:95]
	ds_read_b128 v[206:209], v203 offset:16384
	ds_read_b128 v[210:213], v203 offset:18432
	v_mfma_f32_32x32x16_bf16 v[64:79], v[128:131], v[148:151], v[64:79]
	ds_read_b128 v[214:217], v203 offset:20480
	ds_read_b128 v[218:221], v203 offset:22528
	v_mfma_f32_32x32x16_bf16 v[48:63], v[132:135], v[136:139], v[48:63]
	v_mfma_f32_32x32x16_bf16 v[32:47], v[132:135], v[140:143], v[32:47]
	v_mfma_f32_32x32x16_bf16 v[16:31], v[132:135], v[144:147], v[16:31]
	v_mfma_f32_32x32x16_bf16 v[0:15], v[132:135], v[148:151], v[0:15]
	s_waitcnt vmcnt(8)
	s_waitcnt lgkmcnt(0)
	s_barrier
	ds_read_b128 v[128:131], v154 offset:32768
	ds_read_b128 v[132:135], v154 offset:34816
	ds_read_b128 v[136:139], v202 offset:49152
	ds_read_b128 v[140:143], v202 offset:51200
	ds_read_b128 v[144:147], v202 offset:53248
	ds_read_b128 v[148:151], v202 offset:55296
	v_xor_b32_e32 v154, 0x10000, v154
	v_xor_b32_e32 v202, 0x10000, v202
	s_add_u32 m0, s98, 0x10000
	v_mfma_f32_32x32x16_bf16 v[112:127], v[194:197], v[206:209], v[112:127]
	global_load_lds_dwordx4 v[164:165], off
	v_mfma_f32_32x32x16_bf16 v[96:111], v[194:197], v[210:213], v[96:111]
	s_add_u32 m0, s98, 0x12000
	v_mfma_f32_32x32x16_bf16 v[80:95], v[194:197], v[214:217], v[80:95]
	global_load_lds_dwordx4 v[160:161], off
	v_mfma_f32_32x32x16_bf16 v[64:79], v[194:197], v[218:221], v[64:79]
	s_add_u32 m0, s98, 0x14000
	v_mfma_f32_32x32x16_bf16 v[48:63], v[198:201], v[206:209], v[48:63]
	global_load_lds_dwordx4 v[166:167], off
	v_mfma_f32_32x32x16_bf16 v[32:47], v[198:201], v[210:213], v[32:47]
	s_add_u32 m0, s98, 0x16000
	v_mfma_f32_32x32x16_bf16 v[16:31], v[198:201], v[214:217], v[16:31]
	global_load_lds_dwordx4 v[162:163], off
	v_mfma_f32_32x32x16_bf16 v[0:15], v[198:201], v[218:221], v[0:15]
	v_lshl_add_u64 v[164:165], v[164:165], 0, 64
	v_lshl_add_u64 v[160:161], v[160:161], 0, 64
	v_lshl_add_u64 v[166:167], v[166:167], 0, 64
	v_lshl_add_u64 v[162:163], v[162:163], 0, 64
	s_waitcnt lgkmcnt(0)
	v_mfma_f32_32x32x16_bf16 v[112:127], v[128:131], v[136:139], v[112:127]
	v_mfma_f32_32x32x16_bf16 v[96:111], v[128:131], v[140:143], v[96:111]
	ds_read_b128 v[194:197], v193 offset:32768
	ds_read_b128 v[198:201], v193 offset:34816
	v_mfma_f32_32x32x16_bf16 v[80:95], v[128:131], v[144:147], v[80:95]
	ds_read_b128 v[206:209], v203 offset:49152
	ds_read_b128 v[210:213], v203 offset:51200
	v_mfma_f32_32x32x16_bf16 v[64:79], v[128:131], v[148:151], v[64:79]
	ds_read_b128 v[214:217], v203 offset:53248
	ds_read_b128 v[218:221], v203 offset:55296
	v_mfma_f32_32x32x16_bf16 v[48:63], v[132:135], v[136:139], v[48:63]
	v_mfma_f32_32x32x16_bf16 v[32:47], v[132:135], v[140:143], v[32:47]
	v_mfma_f32_32x32x16_bf16 v[16:31], v[132:135], v[144:147], v[16:31]
	v_mfma_f32_32x32x16_bf16 v[0:15], v[132:135], v[148:151], v[0:15]
	v_xor_b32_e32 v193, 0x10000, v193
	v_xor_b32_e32 v203, 0x10000, v203
	s_waitcnt vmcnt(8)
	s_waitcnt lgkmcnt(0)
	s_mov_b32 s99, 6
